# pk4 + packed subtract (cmp softmax x-max) and src0-broadcast multiplies as scalar pairs
# baseline (speedup 1.0000x reference)
.LBB0_217:
	s_lshl_b32 s10, s64, 8
	s_and_b32 s8, s64, 0xfffffe
	s_cmp_eq_u32 s8, 6
	v_cmp_lt_i32_e32 vcc, s10, v89
	s_cselect_b64 s[8:9], -1, 0
	s_or_b64 s[8:9], vcc, s[8:9]
	s_cmp_lg_u32 s63, 0
	s_cselect_b64 s[48:49], -1, 0
	s_and_b64 vcc, s[48:49], s[8:9]
	v_cndmask_b32_e32 v70, 1.0, v184, vcc
	s_waitcnt vmcnt(0)
	v_mul_f32_e32 v0, v76, v70
	v_mul_f32_e32 v118, v0, v4
	v_mul_f32_e32 v119, v0, v5
	v_mul_f32_e32 v116, v0, v2
	v_mul_f32_e32 v117, v0, v3
	v_add_u32_e32 v114, v83, v84
	v_mul_f32_e32 v0, v79, v70
	ds_write_b128 v114, v[116:119]
	v_mul_f32_e32 v118, v0, v8
	v_mul_f32_e32 v119, v0, v9
	v_mul_f32_e32 v116, v0, v6
	v_mul_f32_e32 v117, v0, v7
	v_mul_f32_e32 v0, v82, v70
	ds_write_b128 v95, v[116:119] offset:8320
	v_mul_f32_e32 v118, v0, v12
	v_mul_f32_e32 v119, v0, v13
	v_mul_f32_e32 v116, v0, v10
	v_mul_f32_e32 v117, v0, v11
	v_mul_f32_e32 v0, v90, v70
	ds_write_b128 v96, v[116:119] offset:16640
	v_mul_f32_e32 v118, v0, v16
	v_mul_f32_e32 v119, v0, v17
	v_mul_f32_e32 v116, v0, v14
	v_mul_f32_e32 v117, v0, v15
	v_mul_f32_e32 v0, v102, v70
	ds_write_b128 v97, v[116:119] offset:24960
	v_mul_f32_e32 v118, v0, v20
	v_mul_f32_e32 v119, v0, v21
	v_mul_f32_e32 v116, v0, v18
	v_mul_f32_e32 v117, v0, v19
	v_mul_f32_e32 v0, v70, v104
	ds_write_b128 v98, v[116:119] offset:33280
	v_mul_f32_e32 v118, v0, v24
	v_mul_f32_e32 v119, v0, v25
	v_mul_f32_e32 v116, v0, v22
	v_mul_f32_e32 v117, v0, v23
	v_mul_f32_e32 v0, v70, v107
	ds_write_b128 v99, v[116:119] offset:41600
	v_mul_f32_e32 v118, v0, v36
	v_mul_f32_e32 v119, v0, v37
	v_mul_f32_e32 v116, v0, v34
	v_mul_f32_e32 v117, v0, v35
	v_mul_f32_e32 v0, v70, v110
	v_add_u32_e32 v70, s10, v85
	ds_write_b128 v100, v[116:119] offset:49920
	v_mul_f32_e32 v118, v0, v48
	v_mul_f32_e32 v119, v0, v49
	v_mul_f32_e32 v116, v0, v46
	v_mul_f32_e32 v117, v0, v47
	v_cmp_gt_i32_e32 vcc, s62, v70
	v_lshlrev_b32_e32 v0, 1, v68
	ds_write_b128 v101, v[116:119] offset:58240
	s_waitcnt lgkmcnt(0)
	s_barrier
	s_and_saveexec_b64 s[8:9], vcc
	s_cbranch_execz .LBB0_219
	ds_read_b32 v71, v91 offset:6240
	ds_read_b32 v115, v91 offset:7280
	ds_read_b32 v116, v91 offset:4160
	ds_read_b32 v117, v91 offset:5200
	ds_read_b32 v120, v91 offset:2080
	ds_read_b32 v121, v91 offset:3120
	ds_read_b32 v122, v91
	ds_read_b32 v123, v91 offset:1040
	s_waitcnt lgkmcnt(6)
	v_cvt_pk_bf16_f32 v119, v71, v115
	v_ashrrev_i32_e32 v115, 31, v70
	v_mad_u64_u32 v[70:71], s[48:49], s61, v70, 0
	s_waitcnt lgkmcnt(4)
	v_cvt_pk_bf16_f32 v118, v116, v117
	s_waitcnt lgkmcnt(2)
	v_cvt_pk_bf16_f32 v117, v120, v121
	v_mov_b32_e32 v120, v71
	v_mad_u64_u32 v[120:121], s[48:49], s61, v115, v[120:121]
	v_mov_b32_e32 v71, v120
	v_lshl_add_u64 v[70:71], v[70:71], 1, s[24:25]
	s_mov_b32 s27, s81
	s_lshl_b32 s48, s70, 6
	v_lshl_add_u64 v[70:71], s[26:27], 1, v[70:71]
	s_ashr_i32 s49, s48, 31
	v_lshl_add_u64 v[70:71], s[48:49], 1, v[70:71]
	s_waitcnt lgkmcnt(0)
	v_cvt_pk_bf16_f32 v116, v122, v123
	v_lshl_add_u64 v[70:71], v[70:71], 0, v[0:1]
	global_store_dwordx4 v[70:71], v[116:119], off

.LBB0_308:
	s_lshl_b32 s8, s73, 8
	s_and_b32 s6, s73, 0xfffffe
	s_cmp_eq_u32 s6, 6
	v_cmp_lt_i32_e32 vcc, s8, v89
	s_cselect_b64 s[6:7], -1, 0
	s_or_b64 vcc, vcc, s[6:7]
	v_cndmask_b32_e32 v70, 1.0, v184, vcc
	v_cndmask_b32_e64 v71, v70, 1.0, s[46:47]
	v_mul_f32_e32 v70, v71, v103
	v_mul_f32_e32 v118, v28, v70
	v_mul_f32_e32 v119, v29, v70
	v_mul_f32_e32 v116, v26, v70
	v_mul_f32_e32 v117, v27, v70
	v_mul_f32_e32 v70, v71, v105
	ds_write_b128 v114, v[116:119]
	v_mul_f32_e32 v116, v32, v70
	v_mul_f32_e32 v117, v33, v70
	v_mul_f32_e32 v114, v30, v70
	v_mul_f32_e32 v115, v31, v70
	v_mul_f32_e32 v70, v71, v106
	ds_write_b128 v95, v[114:117] offset:8320
	v_mul_f32_e32 v116, v70, v40
	v_mul_f32_e32 v117, v70, v41
	v_mul_f32_e32 v114, v70, v38
	v_mul_f32_e32 v115, v70, v39
	v_mul_f32_e32 v70, v71, v108
	ds_write_b128 v96, v[114:117] offset:16640
	v_mul_f32_e32 v116, v70, v44
	v_mul_f32_e32 v117, v70, v45
	v_mul_f32_e32 v114, v70, v42
	v_mul_f32_e32 v115, v70, v43
	v_mul_f32_e32 v70, v71, v109
	ds_write_b128 v97, v[114:117] offset:24960
	v_mul_f32_e32 v116, v70, v52
	v_mul_f32_e32 v117, v70, v53
	v_mul_f32_e32 v114, v70, v50
	v_mul_f32_e32 v115, v70, v51
	v_mul_f32_e32 v70, v71, v111
	ds_write_b128 v98, v[114:117] offset:33280
	v_mul_f32_e32 v116, v70, v56
	v_mul_f32_e32 v117, v70, v57
	v_mul_f32_e32 v114, v70, v54
	v_mul_f32_e32 v115, v70, v55
	v_mul_f32_e32 v70, v71, v112
	ds_write_b128 v99, v[114:117] offset:41600
	v_mul_f32_e32 v116, v70, v60
	v_mul_f32_e32 v117, v70, v61
	v_mul_f32_e32 v114, v70, v58
	v_mul_f32_e32 v115, v70, v59
	v_mul_f32_e32 v70, v71, v113
	ds_write_b128 v100, v[114:117] offset:49920
	v_mul_f32_e32 v116, v70, v64
	v_mul_f32_e32 v117, v70, v65
	v_mul_f32_e32 v114, v70, v62
	v_mul_f32_e32 v115, v70, v63
	v_add_u32_e32 v70, s8, v85
	v_cmp_gt_i32_e32 vcc, s71, v70
	ds_write_b128 v101, v[114:117] offset:58240
	s_waitcnt lgkmcnt(0)
	s_barrier
	s_and_saveexec_b64 s[6:7], vcc
	s_cbranch_execz .LBB0_310
	ds_read_b32 v71, v91 offset:6240
	ds_read_b32 v114, v91 offset:7280
	ds_read_b32 v115, v91 offset:4160
	ds_read_b32 v116, v91 offset:5200
	ds_read_b32 v118, v91 offset:2080
	ds_read_b32 v119, v91 offset:3120
	ds_read_b32 v120, v91
	ds_read_b32 v121, v91 offset:1040
	s_waitcnt lgkmcnt(6)
	v_cvt_pk_bf16_f32 v117, v71, v114
	v_ashrrev_i32_e32 v71, 31, v70
	s_waitcnt lgkmcnt(4)
	v_cvt_pk_bf16_f32 v116, v115, v116
	s_waitcnt lgkmcnt(2)
	v_cvt_pk_bf16_f32 v115, v118, v119
	v_mul_lo_u32 v118, s41, v70
	v_mul_lo_u32 v119, s40, v71
	v_mad_u64_u32 v[70:71], s[46:47], s40, v70, 0
	v_add3_u32 v71, v71, v119, v118
	v_lshl_add_u64 v[70:71], v[70:71], 1, s[42:43]
	s_lshl_b32 s46, s72, 6
	v_lshl_add_u64 v[70:71], s[44:45], 1, v[70:71]
	s_ashr_i32 s47, s46, 31
	v_lshl_add_u64 v[70:71], s[46:47], 1, v[70:71]
	s_waitcnt lgkmcnt(0)
	v_cvt_pk_bf16_f32 v114, v120, v121
	v_lshl_add_u64 v[70:71], v[70:71], 0, v[0:1]
	global_store_dwordx4 v[70:71], v[114:117], off

.LBB0_571:
	s_and_b32 s42, s48, 0x1e00
	s_ashr_i32 s40, s50, 4
	v_add_u32_e32 v2, s42, v35
	s_and_b32 s42, s27, 0xffffe000
	s_and_b32 s41, s40, 7
	v_add_u32_e32 v3, s42, v2
	v_mov_b64_e32 v[14:15], s[30:31]
	v_mad_i64_i32 v[14:15], s[42:43], v3, s90, v[14:15]
	s_lshl_b32 s80, s41, 1
	v_lshl_add_u64 v[14:15], v[14:15], 0, s[80:81]
	s_or_b32 s80, s41, s33
	v_add_co_u32_e32 v14, vcc, 0x2000, v14
	s_lshl_b64 s[42:43], s[80:81], 2
	s_nop 0
	v_addc_co_u32_e32 v15, vcc, 0, v15, vcc
	s_waitcnt lgkmcnt(0)
	s_add_u32 s42, s0, s42
	global_load_ushort v3, v[14:15], off offset:1536
	s_addc_u32 s43, s1, s43
	global_load_dword v13, v1, s[42:43]
	s_mov_b32 s41, 0xbfb8aa3b
	s_waitcnt vmcnt(1)
	v_lshlrev_b32_e32 v3, 16, v3
	s_waitcnt vmcnt(0)
	v_add_f32_e32 v13, v13, v3
	v_min_f32_e32 v3, 0, v13
	v_mul_f32_e64 v13, |v13|, s41
	v_exp_f32_e32 v13, v13
	s_mov_b32 s41, 0x3f2aaaab
	v_add_f32_e32 v16, 1.0, v13
	v_add_f32_e32 v14, -1.0, v16
	v_sub_f32_e32 v15, v14, v16
	v_add_f32_e32 v15, 1.0, v15
	v_sub_f32_e32 v14, v13, v14
	v_add_f32_e32 v17, v14, v15
	v_frexp_mant_f32_e32 v14, v16
	v_cmp_gt_f32_e32 vcc, s41, v14
	v_cvt_f64_f32_e32 v[14:15], v16
	v_frexp_exp_i32_f64_e32 v14, v[14:15]
	v_subbrev_co_u32_e32 v22, vcc, 0, v14, vcc
	v_sub_u32_e32 v14, 0, v22
	v_ldexp_f32 v15, v16, v14
	v_add_f32_e32 v16, -1.0, v15
	v_add_f32_e32 v18, 1.0, v15
	v_ldexp_f32 v14, v17, v14
	v_add_f32_e32 v17, 1.0, v16
	v_add_f32_e32 v19, -1.0, v18
	v_sub_f32_e32 v17, v15, v17
	v_sub_f32_e32 v15, v15, v19
	v_add_f32_e32 v17, v14, v17
	v_add_f32_e32 v14, v14, v15
	v_add_f32_e32 v23, v18, v14
	v_rcp_f32_e32 v25, v23
	v_sub_f32_e32 v15, v23, v18
	v_sub_f32_e32 v24, v14, v15
	v_add_f32_e32 v15, v16, v17
	v_mul_f32_e32 v27, v15, v25
	v_sub_f32_e32 v14, v15, v16
	v_mul_f32_e32 v16, v23, v27
	v_fma_f32 v18, v27, v23, -v16
	v_fmac_f32_e32 v18, v27, v24
	v_sub_f32_e32 v26, v17, v14
	v_add_f32_e32 v14, v16, v18
	v_sub_f32_e32 v17, v15, v14
	v_sub_f32_e32 v20, v14, v16
	v_sub_f32_e32 v21, v15, v17
	v_mov_b32_e32 v19, v14
	v_sub_f32_e32 v14, v20, v18
	v_sub_f32_e32 v15, v21, v19
	s_mov_b32 s41, 0x3f317218
	v_add_f32_e32 v15, v26, v15
	v_add_f32_e32 v14, v14, v15
	v_add_f32_e32 v15, v17, v14
	v_mul_f32_e32 v26, v25, v15
	v_mul_f32_e32 v16, v23, v26
	v_fma_f32 v18, v26, v23, -v16
	v_fmac_f32_e32 v18, v26, v24
	v_sub_f32_e32 v17, v17, v15
	v_add_f32_e32 v23, v14, v17
	v_add_f32_e32 v14, v16, v18
	v_sub_f32_e32 v17, v15, v14
	v_sub_f32_e32 v20, v14, v16
	v_sub_f32_e32 v21, v15, v17
	v_mov_b32_e32 v19, v14
	v_sub_f32_e32 v14, v20, v18
	v_sub_f32_e32 v15, v21, v19
	s_nop 0
	v_add_f32_e32 v15, v23, v15
	v_add_f32_e32 v14, v14, v15
	v_add_f32_e32 v15, v27, v26
	v_add_f32_e32 v14, v17, v14
	v_sub_f32_e32 v16, v15, v27
	v_mul_f32_e32 v14, v25, v14
	v_sub_f32_e32 v16, v26, v16
	v_add_f32_e32 v16, v16, v14
	v_add_f32_e32 v18, v15, v16
	v_mul_f32_e32 v19, v18, v18
	v_mov_b32_e32 v14, 0x3ecc95a3
	v_fmamk_f32 v14, v19, 0x3e9b6dac, v14
	v_fmaak_f32 v161, v19, v14, 0x3f2aaada
	v_cvt_f32_i32_e32 v14, v22
	v_sub_f32_e32 v15, v18, v15
	v_sub_f32_e32 v15, v16, v15
	v_ldexp_f32 v20, v15, 1
	v_mul_f32_e32 v15, v18, v19
	v_ldexp_f32 v17, v18, 1
	v_mul_f32_e32 v18, v14, v160
	v_mul_f32_e32 v19, v15, v161
	s_nop 0
	v_fma_f32 v16, v14, s41, -v18
	v_fmac_f32_e32 v16, 0xb102e308, v14
	v_add_f32_e32 v14, v18, v16
	v_add_f32_e32 v15, v19, v17
	s_mov_b32 s41, 0x7f800000
	v_sub_f32_e32 v17, v15, v17
	v_sub_f32_e32 v17, v19, v17
	v_add_f32_e32 v21, v20, v17
	v_mov_b32_e32 v20, v18
	v_sub_f32_e32 v18, v14, v18
	v_sub_f32_e32 v19, v15, v19
	v_add_f32_e32 v22, v14, v20
	v_add_f32_e32 v23, v15, v21
	v_mov_b32_e32 v17, v14
	v_mov_b32_e32 v19, v23
	v_sub_f32_e32 v24, v16, v18
	v_sub_f32_e32 v25, v17, v19
	v_add_f32_e32 v16, v16, v18
	v_add_f32_e32 v17, v17, v19
	v_mov_b32_e32 v20, v21
	v_pk_add_f32 v[18:19], v[16:17], v[14:15] op_sel:[1,0] op_sel_hi:[0,1] neg_lo:[0,1] neg_hi:[0,1]
	v_sub_f32_e32 v26, v22, v18
	v_sub_f32_e32 v27, v23, v18
	v_mov_b32_e32 v22, v23
	v_mov_b32_e32 v23, v17
	v_pk_mov_b32 v[18:19], v[14:15], v[18:19] op_sel:[1,0]
	v_mov_b32_e32 v21, v14
	v_sub_f32_e32 v18, v22, v18
	v_sub_f32_e32 v19, v23, v19
	v_mov_b32_e32 v26, v24
	v_sub_f32_e32 v14, v20, v18
	v_sub_f32_e32 v15, v21, v19
	v_mov_b32_e32 v25, v17
	v_add_f32_e32 v18, v26, v14
	v_add_f32_e32 v19, v27, v15
	v_cmp_neq_f32_e32 vcc, s41, v13
	v_pk_add_f32 v[20:21], v[18:19], v[18:19] op_sel:[0,1] op_sel_hi:[1,0]
	s_mov_b32 s41, 0x33800000
	v_pk_add_f32 v[16:17], v[16:17], v[20:21] op_sel:[1,0] op_sel_hi:[0,1]
	v_mov_b32_e32 v19, v16
	v_sub_f32_e32 v22, v18, v24
	v_sub_f32_e32 v23, v19, v25
	v_mov_b32_e32 v15, v20
	v_sub_f32_e32 v17, v18, v22
	v_sub_f32_e32 v14, v14, v22
	v_sub_f32_e32 v15, v15, v23
	v_sub_f32_e32 v17, v24, v17
	v_add_f32_e32 v14, v14, v17
	v_add_f32_e32 v14, v14, v15
	v_add_f32_e32 v14, v16, v14
	v_mov_b32_e32 v15, 0x7f800000
	v_cndmask_b32_e32 v14, v15, v14, vcc
	v_cmp_ngt_f32_e32 vcc, -1.0, v13
	v_mov_b32_e32 v15, 0x7fc00000
	s_nop 0
	v_cndmask_b32_e32 v14, v15, v14, vcc
	v_cmp_neq_f32_e32 vcc, -1.0, v13
	s_nop 1
	v_cndmask_b32_e32 v14, v185, v14, vcc
	v_cmp_lt_f32_e64 vcc, |v13|, s41
	s_nop 1
	v_cndmask_b32_e32 v13, v14, v13, vcc
	v_sub_f32_e32 v3, v3, v13
	ds_write_b32 v0, v3
	s_waitcnt lgkmcnt(0)
	s_barrier
	ds_read_b32 v3, v0
	s_and_saveexec_b64 s[42:43], s[8:9]
	s_cbranch_execz .LBB0_573
	ds_read_b32 v13, v4
	s_waitcnt lgkmcnt(0)
	v_add_f32_e32 v3, v3, v13

.LBB0_843:
	s_nop 6
	v_max3_f32 v0, v34, v35, v36
	s_nop 0
	v_max3_f32 v59, v18, v19, v20
	v_max3_f32 v0, v0, v37, v38
	v_max3_f32 v59, v59, v21, v22
	v_max3_f32 v0, v0, v39, v40
	v_max3_f32 v59, v59, v23, v24
	v_max3_f32 v0, v0, v41, v42
	v_max3_f32 v59, v59, v25, v26
	v_max3_f32 v0, v0, v43, v44
	v_max3_f32 v59, v59, v27, v28
	v_max3_f32 v0, v0, v45, v46
	v_max3_f32 v59, v59, v29, v30
	v_max_f32_e32 v62, v33, v33
	v_max_f32_e32 v63, v49, v49
	v_max3_f32 v0, v0, v47, v48
	v_max3_f32 v59, v59, v31, v32
	v_max_f32_e32 v62, v63, v62
	v_max3_f32 v0, v0, v59, v62
	v_mov_b32_e32 v59, v0
	s_nop 1
	v_permlane32_swap_b32_e32 v0, v59
	v_max_f32_e32 v59, v59, v59
	v_max_f32_e32 v0, v0, v0
	v_max_f32_e32 v0, v0, v59
	v_cmp_lt_f32_e32 vcc, s91, v0
	s_cbranch_vccz .LBB0_845
	v_max_f32_e32 v0, v0, v0
	v_max_f32_e32 v0, 0, v0
	v_exp_f32_e64 v59, -v0
	v_add_f32_e32 v61, v61, v0
	v_sub_f32_e32 v34, v34, v0
	v_sub_f32_e32 v35, v35, v0
	v_sub_f32_e32 v18, v18, v0
	v_sub_f32_e32 v19, v19, v0
	v_mul_f32_e32 v60, v60, v59
	v_sub_f32_e32 v36, v36, v0
	v_sub_f32_e32 v37, v37, v0
	v_sub_f32_e32 v20, v20, v0
	v_sub_f32_e32 v21, v21, v0
	v_sub_f32_e32 v38, v38, v0
	v_sub_f32_e32 v39, v39, v0
	v_sub_f32_e32 v22, v22, v0
	v_sub_f32_e32 v23, v23, v0
	v_sub_f32_e32 v40, v40, v0
	v_sub_f32_e32 v41, v41, v0
	v_sub_f32_e32 v24, v24, v0
	v_sub_f32_e32 v25, v25, v0
	v_sub_f32_e32 v42, v42, v0
	v_sub_f32_e32 v43, v43, v0
	v_sub_f32_e32 v26, v26, v0
	v_sub_f32_e32 v27, v27, v0
	v_sub_f32_e32 v44, v44, v0
	v_sub_f32_e32 v45, v45, v0
	v_sub_f32_e32 v28, v28, v0
	v_sub_f32_e32 v29, v29, v0
	v_sub_f32_e32 v46, v46, v0
	v_sub_f32_e32 v47, v47, v0
	v_sub_f32_e32 v30, v30, v0
	v_sub_f32_e32 v31, v31, v0
	v_sub_f32_e32 v48, v48, v0
	v_sub_f32_e32 v49, v49, v0
	v_sub_f32_e32 v32, v32, v0
	v_sub_f32_e32 v33, v33, v0
	v_sub_f32_e32 v17, v17, v0
	v_sub_f32_e32 v16, v16, v0
	v_sub_f32_e32 v15, v15, v0
	v_sub_f32_e32 v14, v14, v0
	v_sub_f32_e32 v13, v13, v0
	v_sub_f32_e32 v12, v12, v0
	v_sub_f32_e32 v11, v11, v0
	v_sub_f32_e32 v10, v10, v0
	v_sub_f32_e32 v9, v9, v0
	v_sub_f32_e32 v8, v8, v0
	v_sub_f32_e32 v7, v7, v0
	v_sub_f32_e32 v6, v6, v0
	v_sub_f32_e32 v5, v5, v0
	v_sub_f32_e32 v4, v4, v0
	v_sub_f32_e32 v3, v3, v0
	v_sub_f32_e32 v2, v2, v0

.LBB0_852:
	s_nop 7
	v_max3_f32 v0, v34, v35, v36
	s_nop 0
	v_max3_f32 v59, v18, v19, v20
	v_max3_f32 v0, v0, v37, v38
	v_max3_f32 v59, v59, v21, v22
	v_max3_f32 v0, v0, v39, v40
	v_max3_f32 v59, v59, v23, v24
	v_max3_f32 v0, v0, v41, v42
	v_max3_f32 v59, v59, v25, v26
	v_max3_f32 v0, v0, v43, v44
	v_max3_f32 v59, v59, v27, v28
	v_max3_f32 v0, v0, v45, v46
	v_max3_f32 v59, v59, v29, v30
	v_max_f32_e32 v62, v33, v33
	v_max_f32_e32 v63, v49, v49
	v_max3_f32 v0, v0, v47, v48
	v_max3_f32 v59, v59, v31, v32
	v_max_f32_e32 v62, v63, v62
	v_max3_f32 v0, v0, v59, v62
	v_mov_b32_e32 v59, v0
	s_nop 1
	v_permlane32_swap_b32_e32 v0, v59
	v_max_f32_e32 v59, v59, v59
	v_max_f32_e32 v0, v0, v0
	v_max_f32_e32 v0, v0, v59
	v_cmp_lt_f32_e32 vcc, s91, v0
	s_cbranch_vccz .LBB0_854
	v_max_f32_e32 v0, v0, v0
	v_max_f32_e32 v0, 0, v0
	v_exp_f32_e64 v59, -v0
	v_add_f32_e32 v61, v61, v0
	v_sub_f32_e32 v34, v34, v0
	v_sub_f32_e32 v35, v35, v0
	v_sub_f32_e32 v18, v18, v0
	v_sub_f32_e32 v19, v19, v0
	v_mul_f32_e32 v60, v60, v59
	v_sub_f32_e32 v36, v36, v0
	v_sub_f32_e32 v37, v37, v0
	v_sub_f32_e32 v20, v20, v0
	v_sub_f32_e32 v21, v21, v0
	v_sub_f32_e32 v38, v38, v0
	v_sub_f32_e32 v39, v39, v0
	v_sub_f32_e32 v22, v22, v0
	v_sub_f32_e32 v23, v23, v0
	v_sub_f32_e32 v40, v40, v0
	v_sub_f32_e32 v41, v41, v0
	v_sub_f32_e32 v24, v24, v0
	v_sub_f32_e32 v25, v25, v0
	v_sub_f32_e32 v42, v42, v0
	v_sub_f32_e32 v43, v43, v0
	v_sub_f32_e32 v26, v26, v0
	v_sub_f32_e32 v27, v27, v0
	v_sub_f32_e32 v44, v44, v0
	v_sub_f32_e32 v45, v45, v0
	v_sub_f32_e32 v28, v28, v0
	v_sub_f32_e32 v29, v29, v0
	v_sub_f32_e32 v46, v46, v0
	v_sub_f32_e32 v47, v47, v0
	v_sub_f32_e32 v30, v30, v0
	v_sub_f32_e32 v31, v31, v0
	v_sub_f32_e32 v48, v48, v0
	v_sub_f32_e32 v49, v49, v0
	v_sub_f32_e32 v32, v32, v0
	v_sub_f32_e32 v33, v33, v0
	v_sub_f32_e32 v17, v17, v0
	v_sub_f32_e32 v16, v16, v0
	v_sub_f32_e32 v15, v15, v0
	v_sub_f32_e32 v14, v14, v0
	v_sub_f32_e32 v13, v13, v0
	v_sub_f32_e32 v12, v12, v0
	v_sub_f32_e32 v11, v11, v0
	v_sub_f32_e32 v10, v10, v0
	v_sub_f32_e32 v9, v9, v0
	v_sub_f32_e32 v8, v8, v0
	v_sub_f32_e32 v7, v7, v0
	v_sub_f32_e32 v6, v6, v0
	v_sub_f32_e32 v5, v5, v0
	v_sub_f32_e32 v4, v4, v0
	v_sub_f32_e32 v3, v3, v0
	v_sub_f32_e32 v2, v2, v0

.Lsel_nodiag_0b:
	v_add_u32_e32 v187, s81, v208
	ds_read_b128 v[124:127], v187 offset:9216
	ds_read_b128 v[144:147], v187 offset:13824
	ds_read_b128 v[148:151], v187 offset:9248
	v_exp_f32_e32 v80, v80
	v_exp_f32_e32 v81, v81
	v_exp_f32_e32 v82, v82
	v_exp_f32_e32 v83, v83
	s_waitcnt lgkmcnt(6)
	v_mfma_f32_32x32x16_bf16 v[238:253], v[108:111], v[128:131], v[2:17]
	ds_read_b128 v[108:111], v0 offset:64
	v_exp_f32_e32 v84, v84
	v_exp_f32_e32 v85, v85
	v_exp_f32_e32 v86, v86
	v_exp_f32_e32 v87, v87
	s_waitcnt lgkmcnt(6)
	v_mfma_f32_32x32x16_bf16 v[222:237], v[112:115], v[128:131], v[2:17]
	ds_read_b128 v[112:115], v0 offset:4672
	v_add_f32_e32 v164, 0, v80
	v_add_f32_e32 v165, 0, v81
	v_add_f32_e32 v164, v82, v164
	v_add_f32_e32 v165, v83, v165
	v_cvt_pk_bf16_f32 v80, v80, v81
	v_cvt_pk_bf16_f32 v81, v82, v83
	v_add_f32_e32 v164, v84, v164
	v_add_f32_e32 v165, v85, v165
	v_add_f32_e32 v164, v86, v164
	v_add_f32_e32 v165, v87, v165
	v_cvt_pk_bf16_f32 v82, v84, v85
	v_cvt_pk_bf16_f32 v83, v86, v87
	v_cndmask_b32_e64 v80, v80, 0, s[72:73]
	v_cndmask_b32_e64 v81, v81, 0, s[72:73]
	v_cndmask_b32_e64 v82, v82, 0, s[72:73]
	v_cndmask_b32_e64 v83, v83, 0, s[72:73]
	v_exp_f32_e32 v88, v88
	v_exp_f32_e32 v89, v89
	s_waitcnt lgkmcnt(4)
	v_mfma_f32_32x32x16_bf16 v[48:63], v[124:127], v[80:83], v[48:63]
	ds_read_b128 v[124:127], v187 offset:13856
	v_exp_f32_e32 v90, v90
	v_exp_f32_e32 v91, v91
	s_waitcnt lgkmcnt(4)
	v_mfma_f32_32x32x16_bf16 v[32:47], v[144:147], v[80:83], v[32:47]
	ds_read_b128 v[144:147], v187 offset:9280
	v_exp_f32_e32 v92, v92
	v_exp_f32_e32 v93, v93
	v_mfma_f32_32x32x16_bf16 v[238:253], v[116:119], v[132:135], v[238:253]
	ds_read_b128 v[116:119], v0 offset:96
	v_exp_f32_e32 v94, v94
	v_exp_f32_e32 v95, v95
	v_mfma_f32_32x32x16_bf16 v[222:237], v[120:123], v[132:135], v[222:237]
	ds_read_b128 v[120:123], v0 offset:4704
	v_add_f32_e32 v164, v88, v164
	v_add_f32_e32 v165, v89, v165
	v_add_f32_e32 v164, v90, v164
	v_add_f32_e32 v165, v91, v165
	v_cvt_pk_bf16_f32 v88, v88, v89
	v_cvt_pk_bf16_f32 v89, v90, v91
	v_add_f32_e32 v164, v92, v164
	v_add_f32_e32 v165, v93, v165
	v_add_f32_e32 v164, v94, v164
	v_add_f32_e32 v165, v95, v165
	v_cvt_pk_bf16_f32 v90, v92, v93
	v_cvt_pk_bf16_f32 v91, v94, v95
	v_cndmask_b32_e64 v88, v88, 0, s[72:73]
	v_cndmask_b32_e64 v89, v89, 0, s[72:73]
	v_cndmask_b32_e64 v90, v90, 0, s[72:73]
	v_cndmask_b32_e64 v91, v91, 0, s[72:73]
	v_exp_f32_e32 v64, v64
	v_exp_f32_e32 v65, v65
	s_waitcnt lgkmcnt(6)
	v_mfma_f32_32x32x16_bf16 v[48:63], v[148:151], v[88:91], v[48:63]
	ds_read_b128 v[148:151], v187 offset:13888
	v_exp_f32_e32 v66, v66
	v_exp_f32_e32 v67, v67
	s_waitcnt lgkmcnt(4)
	v_mfma_f32_32x32x16_bf16 v[32:47], v[124:127], v[88:91], v[32:47]
	ds_read_b128 v[124:127], v187 offset:9312
	v_exp_f32_e32 v68, v68
	v_exp_f32_e32 v69, v69
	v_mfma_f32_32x32x16_bf16 v[238:253], v[108:111], v[136:139], v[238:253]
	v_exp_f32_e32 v70, v70
	v_exp_f32_e32 v71, v71
	v_mfma_f32_32x32x16_bf16 v[222:237], v[112:115], v[136:139], v[222:237]
	v_add_f32_e32 v164, v64, v164
	v_add_f32_e32 v165, v65, v165
	v_add_f32_e32 v164, v66, v164
	v_add_f32_e32 v165, v67, v165
	v_cvt_pk_bf16_f32 v64, v64, v65
	v_cvt_pk_bf16_f32 v65, v66, v67
	v_add_f32_e32 v164, v68, v164
	v_add_f32_e32 v165, v69, v165
	v_add_f32_e32 v164, v70, v164
	v_add_f32_e32 v165, v71, v165
	v_cvt_pk_bf16_f32 v66, v68, v69
	v_cvt_pk_bf16_f32 v67, v70, v71
	v_cndmask_b32_e64 v64, v64, 0, s[72:73]
	v_cndmask_b32_e64 v65, v65, 0, s[72:73]
	v_cndmask_b32_e64 v66, v66, 0, s[72:73]
	v_cndmask_b32_e64 v67, v67, 0, s[72:73]
	v_exp_f32_e32 v72, v72
	v_exp_f32_e32 v73, v73
	s_waitcnt lgkmcnt(4)
	v_mfma_f32_32x32x16_bf16 v[48:63], v[144:147], v[64:67], v[48:63]
	ds_read_b128 v[144:147], v187 offset:13920
	v_exp_f32_e32 v74, v74
	v_exp_f32_e32 v75, v75
	s_waitcnt lgkmcnt(2)
	v_mfma_f32_32x32x16_bf16 v[32:47], v[148:151], v[64:67], v[32:47]
	v_exp_f32_e32 v76, v76
	v_exp_f32_e32 v77, v77
	v_mfma_f32_32x32x16_bf16 v[238:253], v[116:119], v[140:143], v[238:253]
	v_exp_f32_e32 v78, v78
	v_exp_f32_e32 v79, v79
	v_mfma_f32_32x32x16_bf16 v[222:237], v[120:123], v[140:143], v[222:237]
	v_add_f32_e32 v164, v72, v164
	v_add_f32_e32 v165, v73, v165
	v_add_f32_e32 v164, v74, v164
	v_add_f32_e32 v165, v75, v165
	v_cvt_pk_bf16_f32 v72, v72, v73
	v_cvt_pk_bf16_f32 v73, v74, v75
	v_add_f32_e32 v164, v76, v164
	v_add_f32_e32 v165, v77, v165
	v_add_f32_e32 v164, v78, v164
	v_add_f32_e32 v165, v79, v165
	v_cvt_pk_bf16_f32 v74, v76, v77
	v_cvt_pk_bf16_f32 v75, v78, v79
	v_cndmask_b32_e64 v72, v72, 0, s[72:73]
	v_cndmask_b32_e64 v73, v73, 0, s[72:73]
	v_cndmask_b32_e64 v74, v74, 0, s[72:73]
	v_cndmask_b32_e64 v75, v75, 0, s[72:73]
	s_nop 1
	s_waitcnt lgkmcnt(1)
	v_mfma_f32_32x32x16_bf16 v[48:63], v[124:127], v[72:75], v[48:63]
	s_waitcnt lgkmcnt(0)
	v_mfma_f32_32x32x16_bf16 v[32:47], v[144:147], v[72:75], v[32:47]
	v_add_f32_e32 v164, v164, v165
	v_cndmask_b32_e64 v164, v164, 0, s[72:73]
	v_add_f32_e32 v106, v106, v164
	v_cmp_lt_f32_e32 vcc, 0x43800000, v164
	s_cbranch_vccz .Lsel_noresc_0b
	s_nop 15
	s_nop 15
	v_mov_b32_e32 v107, v164
	s_nop 1
	v_permlane32_swap_b32_e32 v164, v107
	v_add_f32_e32 v164, v164, v107
	v_log_f32_e32 v160, v164
	s_nop 0
	v_max_f32_e32 v160, 0, v160
	v_exp_f32_e64 v162, -v160
	v_sub_f32_e32 v2, v2, v160
	v_sub_f32_e32 v3, v3, v160
	v_sub_f32_e32 v4, v4, v160
	v_sub_f32_e32 v5, v5, v160
	v_sub_f32_e32 v6, v6, v160
	v_sub_f32_e32 v7, v7, v160
	v_sub_f32_e32 v8, v8, v160
	v_sub_f32_e32 v9, v9, v160
	v_sub_f32_e32 v10, v10, v160
	v_sub_f32_e32 v11, v11, v160
	v_sub_f32_e32 v12, v12, v160
	v_sub_f32_e32 v13, v13, v160
	v_sub_f32_e32 v14, v14, v160
	v_sub_f32_e32 v15, v15, v160
	v_sub_f32_e32 v16, v16, v160
	v_sub_f32_e32 v17, v17, v160
	v_mul_f32_e32 v106, v106, v162
	v_mul_f32_e32 v48, v48, v162
	v_mul_f32_e32 v49, v49, v162
	v_mul_f32_e32 v32, v32, v162
	v_mul_f32_e32 v33, v33, v162
	v_mul_f32_e32 v50, v50, v162
	v_mul_f32_e32 v51, v51, v162
	v_mul_f32_e32 v34, v34, v162
	v_mul_f32_e32 v35, v35, v162
	v_mul_f32_e32 v52, v52, v162
	v_mul_f32_e32 v53, v53, v162
	v_mul_f32_e32 v36, v36, v162
	v_mul_f32_e32 v37, v37, v162
	v_mul_f32_e32 v54, v54, v162
	v_mul_f32_e32 v55, v55, v162
	v_mul_f32_e32 v38, v38, v162
	v_mul_f32_e32 v39, v39, v162
	v_mul_f32_e32 v56, v56, v162
	v_mul_f32_e32 v57, v57, v162
	v_mul_f32_e32 v40, v40, v162
	v_mul_f32_e32 v41, v41, v162
	v_mul_f32_e32 v58, v58, v162
	v_mul_f32_e32 v59, v59, v162
	v_mul_f32_e32 v42, v42, v162
	v_mul_f32_e32 v43, v43, v162
	v_mul_f32_e32 v60, v60, v162
	v_mul_f32_e32 v61, v61, v162
	v_mul_f32_e32 v44, v44, v162
	v_mul_f32_e32 v45, v45, v162
	v_mul_f32_e32 v62, v62, v162
	v_mul_f32_e32 v63, v63, v162
	v_mul_f32_e32 v46, v46, v162
	v_mul_f32_e32 v47, v47, v162
	v_sub_f32_e32 v238, v238, v160
	v_sub_f32_e32 v239, v239, v160
	v_sub_f32_e32 v222, v222, v160
	v_sub_f32_e32 v223, v223, v160
	v_sub_f32_e32 v240, v240, v160
	v_sub_f32_e32 v241, v241, v160
	v_sub_f32_e32 v224, v224, v160
	v_sub_f32_e32 v225, v225, v160
	v_sub_f32_e32 v242, v242, v160
	v_sub_f32_e32 v243, v243, v160
	v_sub_f32_e32 v226, v226, v160
	v_sub_f32_e32 v227, v227, v160
	v_sub_f32_e32 v244, v244, v160
	v_sub_f32_e32 v245, v245, v160
	v_sub_f32_e32 v228, v228, v160
	v_sub_f32_e32 v229, v229, v160
	v_sub_f32_e32 v246, v246, v160
	v_sub_f32_e32 v247, v247, v160
	v_sub_f32_e32 v230, v230, v160
	v_sub_f32_e32 v231, v231, v160
	v_sub_f32_e32 v248, v248, v160
	v_sub_f32_e32 v249, v249, v160
	v_sub_f32_e32 v232, v232, v160
	v_sub_f32_e32 v233, v233, v160
	v_sub_f32_e32 v250, v250, v160
	v_sub_f32_e32 v251, v251, v160
	v_sub_f32_e32 v234, v234, v160
	v_sub_f32_e32 v235, v235, v160
	v_sub_f32_e32 v252, v252, v160
	v_sub_f32_e32 v253, v253, v160
	v_sub_f32_e32 v236, v236, v160
	v_sub_f32_e32 v237, v237, v160
	s_nop 1

.Lsel_nodiag_1b:
	v_add_u32_e32 v187, s81, v208
	ds_read_b128 v[124:127], v187 offset:9216
	ds_read_b128 v[144:147], v187 offset:13824
	ds_read_b128 v[148:151], v187 offset:9248
	v_exp_f32_e32 v238, v238
	v_exp_f32_e32 v239, v239
	v_exp_f32_e32 v240, v240
	v_exp_f32_e32 v241, v241
	s_waitcnt lgkmcnt(6)
	v_mfma_f32_32x32x16_bf16 v[80:95], v[108:111], v[128:131], v[2:17]
	ds_read_b128 v[108:111], v0 offset:64
	v_exp_f32_e32 v242, v242
	v_exp_f32_e32 v243, v243
	v_exp_f32_e32 v244, v244
	v_exp_f32_e32 v245, v245
	s_waitcnt lgkmcnt(6)
	v_mfma_f32_32x32x16_bf16 v[64:79], v[112:115], v[128:131], v[2:17]
	ds_read_b128 v[112:115], v0 offset:4672
	v_add_f32_e32 v164, 0, v238
	v_add_f32_e32 v165, 0, v239
	v_add_f32_e32 v164, v240, v164
	v_add_f32_e32 v165, v241, v165
	v_cvt_pk_bf16_f32 v238, v238, v239
	v_cvt_pk_bf16_f32 v239, v240, v241
	v_add_f32_e32 v164, v242, v164
	v_add_f32_e32 v165, v243, v165
	v_add_f32_e32 v164, v244, v164
	v_add_f32_e32 v165, v245, v165
	v_cvt_pk_bf16_f32 v240, v242, v243
	v_cvt_pk_bf16_f32 v241, v244, v245
	v_cndmask_b32_e64 v238, v238, 0, s[72:73]
	v_cndmask_b32_e64 v239, v239, 0, s[72:73]
	v_cndmask_b32_e64 v240, v240, 0, s[72:73]
	v_cndmask_b32_e64 v241, v241, 0, s[72:73]
	v_exp_f32_e32 v246, v246
	v_exp_f32_e32 v247, v247
	s_waitcnt lgkmcnt(4)
	v_mfma_f32_32x32x16_bf16 v[48:63], v[124:127], v[238:241], v[48:63]
	ds_read_b128 v[124:127], v187 offset:13856
	v_exp_f32_e32 v248, v248
	v_exp_f32_e32 v249, v249
	s_waitcnt lgkmcnt(4)
	v_mfma_f32_32x32x16_bf16 v[32:47], v[144:147], v[238:241], v[32:47]
	ds_read_b128 v[144:147], v187 offset:9280
	v_exp_f32_e32 v250, v250
	v_exp_f32_e32 v251, v251
	v_mfma_f32_32x32x16_bf16 v[80:95], v[116:119], v[132:135], v[80:95]
	ds_read_b128 v[116:119], v0 offset:96
	v_exp_f32_e32 v252, v252
	v_exp_f32_e32 v253, v253
	v_mfma_f32_32x32x16_bf16 v[64:79], v[120:123], v[132:135], v[64:79]
	ds_read_b128 v[120:123], v0 offset:4704
	v_add_f32_e32 v164, v246, v164
	v_add_f32_e32 v165, v247, v165
	v_add_f32_e32 v164, v248, v164
	v_add_f32_e32 v165, v249, v165
	v_cvt_pk_bf16_f32 v246, v246, v247
	v_cvt_pk_bf16_f32 v247, v248, v249
	v_add_f32_e32 v164, v250, v164
	v_add_f32_e32 v165, v251, v165
	v_add_f32_e32 v164, v252, v164
	v_add_f32_e32 v165, v253, v165
	v_cvt_pk_bf16_f32 v248, v250, v251
	v_cvt_pk_bf16_f32 v249, v252, v253
	v_cndmask_b32_e64 v246, v246, 0, s[72:73]
	v_cndmask_b32_e64 v247, v247, 0, s[72:73]
	v_cndmask_b32_e64 v248, v248, 0, s[72:73]
	v_cndmask_b32_e64 v249, v249, 0, s[72:73]
	v_exp_f32_e32 v222, v222
	v_exp_f32_e32 v223, v223
	s_waitcnt lgkmcnt(6)
	v_mfma_f32_32x32x16_bf16 v[48:63], v[148:151], v[246:249], v[48:63]
	ds_read_b128 v[148:151], v187 offset:13888
	v_exp_f32_e32 v224, v224
	v_exp_f32_e32 v225, v225
	s_waitcnt lgkmcnt(4)
	v_mfma_f32_32x32x16_bf16 v[32:47], v[124:127], v[246:249], v[32:47]
	ds_read_b128 v[124:127], v187 offset:9312
	v_exp_f32_e32 v226, v226
	v_exp_f32_e32 v227, v227
	v_mfma_f32_32x32x16_bf16 v[80:95], v[108:111], v[136:139], v[80:95]
	v_exp_f32_e32 v228, v228
	v_exp_f32_e32 v229, v229
	v_mfma_f32_32x32x16_bf16 v[64:79], v[112:115], v[136:139], v[64:79]
	v_add_f32_e32 v164, v222, v164
	v_add_f32_e32 v165, v223, v165
	v_add_f32_e32 v164, v224, v164
	v_add_f32_e32 v165, v225, v165
	v_cvt_pk_bf16_f32 v222, v222, v223
	v_cvt_pk_bf16_f32 v223, v224, v225
	v_add_f32_e32 v164, v226, v164
	v_add_f32_e32 v165, v227, v165
	v_add_f32_e32 v164, v228, v164
	v_add_f32_e32 v165, v229, v165
	v_cvt_pk_bf16_f32 v224, v226, v227
	v_cvt_pk_bf16_f32 v225, v228, v229
	v_cndmask_b32_e64 v222, v222, 0, s[72:73]
	v_cndmask_b32_e64 v223, v223, 0, s[72:73]
	v_cndmask_b32_e64 v224, v224, 0, s[72:73]
	v_cndmask_b32_e64 v225, v225, 0, s[72:73]
	v_exp_f32_e32 v230, v230
	v_exp_f32_e32 v231, v231
	s_waitcnt lgkmcnt(4)
	v_mfma_f32_32x32x16_bf16 v[48:63], v[144:147], v[222:225], v[48:63]
	ds_read_b128 v[144:147], v187 offset:13920
	v_exp_f32_e32 v232, v232
	v_exp_f32_e32 v233, v233
	s_waitcnt lgkmcnt(2)
	v_mfma_f32_32x32x16_bf16 v[32:47], v[148:151], v[222:225], v[32:47]
	v_exp_f32_e32 v234, v234
	v_exp_f32_e32 v235, v235
	v_mfma_f32_32x32x16_bf16 v[80:95], v[116:119], v[140:143], v[80:95]
	v_exp_f32_e32 v236, v236
	v_exp_f32_e32 v237, v237
	v_mfma_f32_32x32x16_bf16 v[64:79], v[120:123], v[140:143], v[64:79]
	v_add_f32_e32 v164, v230, v164
	v_add_f32_e32 v165, v231, v165
	v_add_f32_e32 v164, v232, v164
	v_add_f32_e32 v165, v233, v165
	v_cvt_pk_bf16_f32 v230, v230, v231
	v_cvt_pk_bf16_f32 v231, v232, v233
	v_add_f32_e32 v164, v234, v164
	v_add_f32_e32 v165, v235, v165
	v_add_f32_e32 v164, v236, v164
	v_add_f32_e32 v165, v237, v165
	v_cvt_pk_bf16_f32 v232, v234, v235
	v_cvt_pk_bf16_f32 v233, v236, v237
	v_cndmask_b32_e64 v230, v230, 0, s[72:73]
	v_cndmask_b32_e64 v231, v231, 0, s[72:73]
	v_cndmask_b32_e64 v232, v232, 0, s[72:73]
	v_cndmask_b32_e64 v233, v233, 0, s[72:73]
	s_nop 1
	s_waitcnt lgkmcnt(1)
	v_mfma_f32_32x32x16_bf16 v[48:63], v[124:127], v[230:233], v[48:63]
	s_waitcnt lgkmcnt(0)
	v_mfma_f32_32x32x16_bf16 v[32:47], v[144:147], v[230:233], v[32:47]
	v_add_f32_e32 v164, v164, v165
	v_cndmask_b32_e64 v164, v164, 0, s[72:73]
	v_add_f32_e32 v106, v106, v164
	v_cmp_lt_f32_e32 vcc, 0x43800000, v164
	s_cbranch_vccz .Lsel_noresc_1b
	s_nop 15
	s_nop 15
	v_mov_b32_e32 v107, v164
	s_nop 1
	v_permlane32_swap_b32_e32 v164, v107
	v_add_f32_e32 v164, v164, v107
	v_log_f32_e32 v160, v164
	s_nop 0
	v_max_f32_e32 v160, 0, v160
	v_exp_f32_e64 v162, -v160
	v_sub_f32_e32 v2, v2, v160
	v_sub_f32_e32 v3, v3, v160
	v_sub_f32_e32 v4, v4, v160
	v_sub_f32_e32 v5, v5, v160
	v_sub_f32_e32 v6, v6, v160
	v_sub_f32_e32 v7, v7, v160
	v_sub_f32_e32 v8, v8, v160
	v_sub_f32_e32 v9, v9, v160
	v_sub_f32_e32 v10, v10, v160
	v_sub_f32_e32 v11, v11, v160
	v_sub_f32_e32 v12, v12, v160
	v_sub_f32_e32 v13, v13, v160
	v_sub_f32_e32 v14, v14, v160
	v_sub_f32_e32 v15, v15, v160
	v_sub_f32_e32 v16, v16, v160
	v_sub_f32_e32 v17, v17, v160
	v_mul_f32_e32 v106, v106, v162
	v_mul_f32_e32 v48, v48, v162
	v_mul_f32_e32 v49, v49, v162
	v_mul_f32_e32 v32, v32, v162
	v_mul_f32_e32 v33, v33, v162
	v_mul_f32_e32 v50, v50, v162
	v_mul_f32_e32 v51, v51, v162
	v_mul_f32_e32 v34, v34, v162
	v_mul_f32_e32 v35, v35, v162
	v_mul_f32_e32 v52, v52, v162
	v_mul_f32_e32 v53, v53, v162
	v_mul_f32_e32 v36, v36, v162
	v_mul_f32_e32 v37, v37, v162
	v_mul_f32_e32 v54, v54, v162
	v_mul_f32_e32 v55, v55, v162
	v_mul_f32_e32 v38, v38, v162
	v_mul_f32_e32 v39, v39, v162
	v_mul_f32_e32 v56, v56, v162
	v_mul_f32_e32 v57, v57, v162
	v_mul_f32_e32 v40, v40, v162
	v_mul_f32_e32 v41, v41, v162
	v_mul_f32_e32 v58, v58, v162
	v_mul_f32_e32 v59, v59, v162
	v_mul_f32_e32 v42, v42, v162
	v_mul_f32_e32 v43, v43, v162
	v_mul_f32_e32 v60, v60, v162
	v_mul_f32_e32 v61, v61, v162
	v_mul_f32_e32 v44, v44, v162
	v_mul_f32_e32 v45, v45, v162
	v_mul_f32_e32 v62, v62, v162
	v_mul_f32_e32 v63, v63, v162
	v_mul_f32_e32 v46, v46, v162
	v_mul_f32_e32 v47, v47, v162
	v_sub_f32_e32 v80, v80, v160
	v_sub_f32_e32 v81, v81, v160
	v_sub_f32_e32 v64, v64, v160
	v_sub_f32_e32 v65, v65, v160
	v_sub_f32_e32 v82, v82, v160
	v_sub_f32_e32 v83, v83, v160
	v_sub_f32_e32 v66, v66, v160
	v_sub_f32_e32 v67, v67, v160
	v_sub_f32_e32 v84, v84, v160
	v_sub_f32_e32 v85, v85, v160
	v_sub_f32_e32 v68, v68, v160
	v_sub_f32_e32 v69, v69, v160
	v_sub_f32_e32 v86, v86, v160
	v_sub_f32_e32 v87, v87, v160
	v_sub_f32_e32 v70, v70, v160
	v_sub_f32_e32 v71, v71, v160
	v_sub_f32_e32 v88, v88, v160
	v_sub_f32_e32 v89, v89, v160
	v_sub_f32_e32 v72, v72, v160
	v_sub_f32_e32 v73, v73, v160
	v_sub_f32_e32 v90, v90, v160
	v_sub_f32_e32 v91, v91, v160
	v_sub_f32_e32 v74, v74, v160
	v_sub_f32_e32 v75, v75, v160
	v_sub_f32_e32 v92, v92, v160
	v_sub_f32_e32 v93, v93, v160
	v_sub_f32_e32 v76, v76, v160
	v_sub_f32_e32 v77, v77, v160
	v_sub_f32_e32 v94, v94, v160
	v_sub_f32_e32 v95, v95, v160
	v_sub_f32_e32 v78, v78, v160
	v_sub_f32_e32 v79, v79, v160
	s_nop 1

.LBB0_1475:
	s_ashr_i32 s3, s2, 31
	s_lshl_b64 s[0:1], s[2:3], 6
	s_add_u32 s0, s4, s0
	s_addc_u32 s1, s5, s1
	global_load_dwordx4 v[100:103], v97, s[0:1] offset:48
	global_load_dwordx4 v[104:107], v97, s[0:1] offset:32
	global_load_dwordx4 v[108:111], v97, s[0:1] offset:16
	global_load_dwordx4 v[112:115], v97, s[0:1]
	s_lshl_b64 s[0:1], s[2:3], 12
	s_add_i32 s16, s7, s2
	s_cmpk_lt_i32 s16, 0x4000
	s_cselect_b32 s8, s16, s2
	s_ashr_i32 s9, s8, 31
	s_lshl_b64 s[10:11], s[8:9], 6
	s_add_u32 s22, s4, s10
	s_addc_u32 s23, s5, s11
	s_lshl_b64 s[24:25], s[8:9], 12
	s_add_i32 s12, s19, s2
	s_cmpk_lt_i32 s12, 0x4000
	s_cselect_b64 s[14:15], -1, 0
	s_and_b64 s[8:9], s[14:15], exec
	s_cselect_b32 s8, s12, s2
	s_ashr_i32 s9, s8, 31
	s_lshl_b64 s[10:11], s[8:9], 6
	s_add_u32 s26, s4, s10
	s_addc_u32 s27, s5, s11
	s_lshl_b64 s[28:29], s[8:9], 12
	s_add_i32 s8, s20, s2
	s_cmpk_lt_i32 s8, 0x4000
	s_cselect_b64 s[10:11], -1, 0
	s_and_b64 s[30:31], s[10:11], exec
	s_cselect_b32 s30, s8, s2
	s_ashr_i32 s31, s30, 31
	s_lshl_b64 s[34:35], s[30:31], 6
	s_add_u32 s34, s4, s34
	s_addc_u32 s35, s5, s35
	global_load_dwordx4 v[116:119], v97, s[34:35]
	global_load_dwordx4 v[120:123], v97, s[34:35] offset:16
	global_load_dwordx4 v[124:127], v97, s[34:35] offset:32
	global_load_dwordx4 v[128:131], v97, s[34:35] offset:48
	s_waitcnt vmcnt(0)
	v_lshl_add_u64 v[148:149], v[98:99], 0, s[0:1]
	v_lshl_add_u64 v[16:17], v[98:99], 0, s[24:25]
	global_load_dwordx4 v[132:135], v[148:149], off
	global_load_dwordx4 v[136:139], v[148:149], off offset:1024
	global_load_dwordx4 v[140:143], v[148:149], off offset:2048
	global_load_dwordx4 v[144:147], v[148:149], off offset:3072
	global_load_dwordx4 v[80:83], v97, s[22:23] offset:48
	global_load_dwordx4 v[84:87], v97, s[22:23] offset:32
	global_load_dwordx4 v[88:91], v97, s[22:23] offset:16
	global_load_dwordx4 v[92:95], v97, s[22:23]
	global_load_dwordx4 v[76:79], v[16:17], off
	global_load_dwordx4 v[72:75], v[16:17], off offset:1024
	global_load_dwordx4 v[68:71], v[16:17], off offset:2048
	global_load_dwordx4 v[64:67], v[16:17], off offset:3072
	global_load_dwordx4 v[48:51], v97, s[26:27] offset:48
	global_load_dwordx4 v[52:55], v97, s[26:27] offset:32
	global_load_dwordx4 v[56:59], v97, s[26:27] offset:16
	global_load_dwordx4 v[60:63], v97, s[26:27]
	v_lshl_add_u64 v[16:17], v[98:99], 0, s[28:29]
	s_lshl_b64 s[0:1], s[30:31], 12
	global_load_dwordx4 v[44:47], v[16:17], off
	global_load_dwordx4 v[40:43], v[16:17], off offset:1024
	global_load_dwordx4 v[36:39], v[16:17], off offset:2048
	global_load_dwordx4 v[32:35], v[16:17], off offset:3072
	v_lshl_add_u64 v[16:17], v[98:99], 0, s[0:1]
	global_load_dwordx4 v[28:31], v[16:17], off
	global_load_dwordx4 v[24:27], v[16:17], off offset:1024
	global_load_dwordx4 v[20:23], v[16:17], off offset:2048
	s_nop 0
	global_load_dwordx4 v[16:19], v[16:17], off offset:3072
	s_cmpk_gt_i32 s16, 0x3fff
	v_add_f32_e32 v104, v104, v105
	v_add_f32_e32 v106, v106, v107
	v_mov_b32_e32 v150, v113
	v_mov_b32_e32 v151, v114
	v_mov_b32_e32 v113, v115
	v_mov_b32_e32 v114, v109
	v_mov_b32_e32 v115, v110
	v_mov_b32_e32 v109, v111
	v_mov_b32_e32 v105, v102
	v_mov_b32_e32 v107, v103
	v_add_f32_e32 v102, v150, v112
	v_add_f32_e32 v103, v151, v113
	v_add_f32_e32 v108, v114, v108
	v_add_f32_e32 v109, v115, v109
	v_add_f32_e32 v104, v104, v106
	v_add_f32_e32 v105, v105, v107
	v_pk_add_f32 v[102:103], v[102:103], v[102:103] op_sel:[0,1] op_sel_hi:[1,0]
	v_pk_add_f32 v[106:107], v[108:109], v[108:109] op_sel:[0,1] op_sel_hi:[1,0]
	v_mov_b32_e32 v103, v100
	v_mov_b32_e32 v107, v101
	v_add_f32_e32 v100, v102, v106
	v_add_f32_e32 v101, v103, v107
	v_mov_b32_e32 v106, v121
	v_add_f32_e32 v100, v100, v104
	v_add_f32_e32 v101, v101, v105
	v_mov_b32_e32 v104, v117
	v_mov_b32_e32 v105, v118
	v_mov_b32_e32 v117, v119
	v_mov_b32_e32 v107, v122
	v_mov_b32_e32 v121, v123
	v_add_f32_e32 v104, v104, v116
	v_add_f32_e32 v105, v105, v117
	v_add_f32_e32 v106, v106, v120
	v_add_f32_e32 v107, v107, v121
	v_pk_add_f32 v[104:105], v[104:105], v[104:105] op_sel:[0,1] op_sel_hi:[1,0]
	v_pk_add_f32 v[106:107], v[106:107], v[106:107] op_sel:[0,1] op_sel_hi:[1,0]
	v_add_f32_e32 v108, v124, v125
	v_add_f32_e32 v110, v126, v127
	v_mov_b32_e32 v109, v130
	v_mov_b32_e32 v111, v131
	v_mov_b32_e32 v105, v128
	v_mov_b32_e32 v107, v129
	v_add_f32_e32 v108, v108, v110
	v_add_f32_e32 v109, v109, v111
	v_add_f32_e32 v104, v104, v106
	v_add_f32_e32 v105, v105, v107
	v_mov_b32_e32 v102, v100
	v_add_f32_e32 v104, v104, v108
	v_add_f32_e32 v105, v105, v109
	s_nop 0
	v_mov_b32_e32 v103, v104
	v_mov_b32_e32 v104, v101
	v_add_f32_e32 v100, v102, v104
	v_add_f32_e32 v101, v103, v105
	s_nop 0
	v_pk_fma_f32 v[100:101], v[100:101], s[6:7], v[96:97] op_sel_hi:[1,0,0]
	s_nop 0
	v_mul_f32_e32 v102, 0x4b800000, v100
	v_cmp_gt_f32_e32 vcc, s21, v100
	v_cmp_gt_f32_e64 s[0:1], s21, v101
	s_nop 0
	v_cndmask_b32_e32 v100, v100, v102, vcc
	v_rsq_f32_e32 v100, v100
	s_nop 0
	v_mul_f32_e32 v102, 0x45800000, v100
	v_cndmask_b32_e32 v100, v100, v102, vcc
	s_waitcnt vmcnt(23)
	v_mul_f32_e32 v102, v100, v132
	v_mul_f32_e32 v103, v100, v133
	v_mul_f32_e32 v104, v100, v134
	v_mul_f32_e32 v105, v100, v135
	v_mul_f32_e32 v104, v2, v104
	v_mul_f32_e32 v105, v3, v105
	v_mul_f32_e32 v102, v0, v102
	v_mul_f32_e32 v103, v1, v103
	global_store_dwordx4 v[148:149], v[102:105], off
	s_waitcnt vmcnt(23)
	s_nop 0
	v_mul_f32_e32 v102, v100, v136
	v_mul_f32_e32 v103, v100, v137
	v_mul_f32_e32 v104, v100, v138
	v_mul_f32_e32 v105, v100, v139
	v_mul_f32_e32 v104, v6, v104
	v_mul_f32_e32 v105, v7, v105
	v_mul_f32_e32 v102, v4, v102
	v_mul_f32_e32 v103, v5, v103
	global_store_dwordx4 v[148:149], v[102:105], off offset:1024
	s_waitcnt vmcnt(23)
	s_nop 0
	v_mul_f32_e32 v102, v100, v140
	v_mul_f32_e32 v103, v100, v141
	v_mul_f32_e32 v104, v100, v142
	v_mul_f32_e32 v105, v100, v143
	v_mul_f32_e32 v104, v10, v104
	v_mul_f32_e32 v105, v11, v105
	v_mul_f32_e32 v102, v8, v102
	v_mul_f32_e32 v103, v9, v103
	global_store_dwordx4 v[148:149], v[102:105], off offset:2048
	s_waitcnt vmcnt(23)
	s_nop 0
	v_mul_f32_e32 v102, v100, v144
	v_mul_f32_e32 v103, v100, v145
	v_mul_f32_e32 v104, v100, v146
	v_mul_f32_e32 v105, v100, v147
	v_mul_f32_e32 v104, v14, v104
	v_mul_f32_e32 v105, v15, v105
	v_mul_f32_e32 v102, v12, v102
	v_mul_f32_e32 v103, v13, v103
	global_store_dwordx4 v[148:149], v[102:105], off offset:3072
	s_cbranch_scc1 .LBB0_1478
	s_waitcnt vmcnt(20)
	v_mov_b32_e32 v102, v93
	v_mov_b32_e32 v103, v94
	v_mov_b32_e32 v93, v95
	v_mov_b32_e32 v94, v89
	v_mov_b32_e32 v95, v90
	v_mov_b32_e32 v89, v91
	v_add_f32_e32 v92, v102, v92
	v_add_f32_e32 v93, v103, v93
	v_add_f32_e32 v88, v94, v88
	v_add_f32_e32 v89, v95, v89
	v_pk_add_f32 v[92:93], v[92:93], v[92:93] op_sel:[0,1] op_sel_hi:[1,0]
	v_pk_add_f32 v[88:89], v[88:89], v[88:89] op_sel:[0,1] op_sel_hi:[1,0]
	v_add_f32_e32 v84, v84, v85
	v_add_f32_e32 v86, v86, v87
	v_mov_b32_e32 v93, v80
	v_mov_b32_e32 v89, v81
	v_mov_b32_e32 v85, v82
	v_mov_b32_e32 v87, v83
	v_add_f32_e32 v80, v92, v88
	v_add_f32_e32 v81, v93, v89
	v_add_f32_e32 v82, v84, v86
	v_add_f32_e32 v83, v85, v87
	s_ashr_i32 s17, s16, 31
	v_add_f32_e32 v80, v80, v82
	v_add_f32_e32 v81, v81, v83
	s_lshl_b64 s[16:17], s[16:17], 12
	v_add_f32_e32 v80, v80, v81
	v_fmamk_f32 v80, v80, 0x3a800000, v96
	v_mul_f32_e32 v81, 0x4b800000, v80
	v_cmp_gt_f32_e32 vcc, s21, v80
	v_lshl_add_u64 v[82:83], v[98:99], 0, s[16:17]
	s_nop 0
	v_cndmask_b32_e32 v80, v80, v81, vcc
	v_rsq_f32_e32 v80, v80
	s_nop 0
	v_mul_f32_e32 v81, 0x45800000, v80
	v_cndmask_b32_e32 v80, v80, v81, vcc
	s_waitcnt vmcnt(19)
	v_mul_f32_e32 v76, v80, v76
	v_mul_f32_e32 v77, v80, v77
	v_mul_f32_e32 v78, v80, v78
	v_mul_f32_e32 v79, v80, v79
	s_waitcnt vmcnt(18)
	v_mul_f32_e32 v72, v80, v72
	v_mul_f32_e32 v73, v80, v73
	v_mul_f32_e32 v74, v80, v74
	v_mul_f32_e32 v75, v80, v75
	s_waitcnt vmcnt(17)
	v_mul_f32_e32 v68, v80, v68
	v_mul_f32_e32 v69, v80, v69
	v_mul_f32_e32 v70, v80, v70
	v_mul_f32_e32 v71, v80, v71
	s_waitcnt vmcnt(16)
	v_mul_f32_e32 v64, v80, v64
	v_mul_f32_e32 v65, v80, v65
	v_mul_f32_e32 v66, v80, v66
	v_mul_f32_e32 v67, v80, v67
	v_mul_f32_e32 v78, v2, v78
	v_mul_f32_e32 v79, v3, v79
	v_mul_f32_e32 v76, v0, v76
	v_mul_f32_e32 v77, v1, v77
	v_mul_f32_e32 v74, v6, v74
	v_mul_f32_e32 v75, v7, v75
	v_mul_f32_e32 v72, v4, v72
	v_mul_f32_e32 v73, v5, v73
	v_mul_f32_e32 v70, v10, v70
	v_mul_f32_e32 v71, v11, v71
	v_mul_f32_e32 v68, v8, v68
	v_mul_f32_e32 v69, v9, v69
	v_mul_f32_e32 v66, v14, v66
	v_mul_f32_e32 v67, v15, v67
	v_mul_f32_e32 v64, v12, v64
	v_mul_f32_e32 v65, v13, v65
	global_store_dwordx4 v[82:83], v[76:79], off
	global_store_dwordx4 v[82:83], v[72:75], off offset:1024
	global_store_dwordx4 v[82:83], v[68:71], off offset:2048
	global_store_dwordx4 v[82:83], v[64:67], off offset:3072
	s_andn2_b64 vcc, exec, s[14:15]
	s_cbranch_vccz .LBB0_1479

.LBB0_1479:
	s_waitcnt vmcnt(12)
	v_mov_b32_e32 v64, v61
	v_mov_b32_e32 v65, v62
	v_mov_b32_e32 v61, v63
	v_mov_b32_e32 v62, v57
	v_mov_b32_e32 v63, v58
	v_mov_b32_e32 v57, v59
	v_add_f32_e32 v60, v64, v60
	v_add_f32_e32 v61, v65, v61
	v_add_f32_e32 v56, v62, v56
	v_add_f32_e32 v57, v63, v57
	v_pk_add_f32 v[60:61], v[60:61], v[60:61] op_sel:[0,1] op_sel_hi:[1,0]
	v_pk_add_f32 v[56:57], v[56:57], v[56:57] op_sel:[0,1] op_sel_hi:[1,0]
	v_add_f32_e32 v52, v52, v53
	v_add_f32_e32 v54, v54, v55
	v_mov_b32_e32 v61, v48
	v_mov_b32_e32 v57, v49
	v_mov_b32_e32 v53, v50
	v_mov_b32_e32 v55, v51
	v_add_f32_e32 v48, v60, v56
	v_add_f32_e32 v49, v61, v57
	v_add_f32_e32 v50, v52, v54
	v_add_f32_e32 v51, v53, v55
	s_ashr_i32 s13, s12, 31
	v_add_f32_e32 v48, v48, v50
	v_add_f32_e32 v49, v49, v51
	s_lshl_b64 s[12:13], s[12:13], 12
	v_add_f32_e32 v48, v48, v49
	v_fmamk_f32 v48, v48, 0x3a800000, v96
	v_mul_f32_e32 v49, 0x4b800000, v48
	v_cmp_gt_f32_e32 vcc, s21, v48
	v_lshl_add_u64 v[50:51], v[98:99], 0, s[12:13]
	s_nop 0
	v_cndmask_b32_e32 v48, v48, v49, vcc
	v_rsq_f32_e32 v48, v48
	s_nop 0
	v_mul_f32_e32 v49, 0x45800000, v48
	v_cndmask_b32_e32 v48, v48, v49, vcc
	s_waitcnt vmcnt(11)
	v_mul_f32_e32 v44, v48, v44
	v_mul_f32_e32 v45, v48, v45
	v_mul_f32_e32 v46, v48, v46
	v_mul_f32_e32 v47, v48, v47
	s_waitcnt vmcnt(10)
	v_mul_f32_e32 v40, v48, v40
	v_mul_f32_e32 v41, v48, v41
	v_mul_f32_e32 v42, v48, v42
	v_mul_f32_e32 v43, v48, v43
	s_waitcnt vmcnt(9)
	v_mul_f32_e32 v36, v48, v36
	v_mul_f32_e32 v37, v48, v37
	v_mul_f32_e32 v38, v48, v38
	v_mul_f32_e32 v39, v48, v39
	s_waitcnt vmcnt(8)
	v_mul_f32_e32 v32, v48, v32
	v_mul_f32_e32 v33, v48, v33
	v_mul_f32_e32 v34, v48, v34
	v_mul_f32_e32 v35, v48, v35
	v_mul_f32_e32 v46, v2, v46
	v_mul_f32_e32 v47, v3, v47
	v_mul_f32_e32 v44, v0, v44
	v_mul_f32_e32 v45, v1, v45
	v_mul_f32_e32 v42, v6, v42
	v_mul_f32_e32 v43, v7, v43
	v_mul_f32_e32 v40, v4, v40
	v_mul_f32_e32 v41, v5, v41
	v_mul_f32_e32 v38, v10, v38
	v_mul_f32_e32 v39, v11, v39
	v_mul_f32_e32 v36, v8, v36
	v_mul_f32_e32 v37, v9, v37
	v_mul_f32_e32 v34, v14, v34
	v_mul_f32_e32 v35, v15, v35
	v_mul_f32_e32 v32, v12, v32
	v_mul_f32_e32 v33, v13, v33
	global_store_dwordx4 v[50:51], v[44:47], off
	global_store_dwordx4 v[50:51], v[40:43], off offset:1024
	global_store_dwordx4 v[50:51], v[36:39], off offset:2048
	global_store_dwordx4 v[50:51], v[32:35], off offset:3072
	s_andn2_b64 vcc, exec, s[10:11]
	s_cbranch_vccnz .LBB0_1474
.LBB0_1480:
	s_waitcnt vmcnt(8)
	v_mul_f32_e32 v32, 0x4b800000, v101
	v_cndmask_b32_e64 v32, v101, v32, s[0:1]
	v_rsq_f32_e32 v32, v32
	s_ashr_i32 s9, s8, 31
	s_lshl_b64 s[8:9], s[8:9], 12
	v_lshl_add_u64 v[34:35], v[98:99], 0, s[8:9]
	v_mul_f32_e32 v33, 0x45800000, v32
	v_cndmask_b32_e64 v32, v32, v33, s[0:1]
	s_waitcnt vmcnt(7)
	v_mul_f32_e32 v28, v32, v28
	v_mul_f32_e32 v29, v32, v29
	v_mul_f32_e32 v30, v32, v30
	v_mul_f32_e32 v31, v32, v31
	s_waitcnt vmcnt(6)
	v_mul_f32_e32 v24, v32, v24
	v_mul_f32_e32 v25, v32, v25
	v_mul_f32_e32 v26, v32, v26
	v_mul_f32_e32 v27, v32, v27
	s_waitcnt vmcnt(5)
	v_mul_f32_e32 v20, v32, v20
	v_mul_f32_e32 v21, v32, v21
	v_mul_f32_e32 v22, v32, v22
	v_mul_f32_e32 v23, v32, v23
	s_waitcnt vmcnt(4)
	v_mul_f32_e32 v16, v32, v16
	v_mul_f32_e32 v17, v32, v17
	v_mul_f32_e32 v18, v32, v18
	v_mul_f32_e32 v19, v32, v19
	v_mul_f32_e32 v30, v2, v30
	v_mul_f32_e32 v31, v3, v31
	v_mul_f32_e32 v28, v0, v28
	v_mul_f32_e32 v29, v1, v29
	v_mul_f32_e32 v26, v6, v26
	v_mul_f32_e32 v27, v7, v27
	v_mul_f32_e32 v24, v4, v24
	v_mul_f32_e32 v25, v5, v25
	v_mul_f32_e32 v22, v10, v22
	v_mul_f32_e32 v23, v11, v23
	v_mul_f32_e32 v20, v8, v20
	v_mul_f32_e32 v21, v9, v21
	v_mul_f32_e32 v18, v14, v18
	v_mul_f32_e32 v19, v15, v19
	v_mul_f32_e32 v16, v12, v16
	v_mul_f32_e32 v17, v13, v17
	global_store_dwordx4 v[34:35], v[28:31], off
	global_store_dwordx4 v[34:35], v[24:27], off offset:1024
	global_store_dwordx4 v[34:35], v[20:23], off offset:2048
	global_store_dwordx4 v[34:35], v[16:19], off offset:3072
	s_branch .LBB0_1474
